# SSD waves 0-3 issue next-step row loads 0-23 before conv segment 3 (registers already dead), leaving an 11-load tail; seg-3 vmcnt waits re-derived
# baseline (speedup 1.0000x reference)
; __device__ __forceinline__ float bflo(unsigned u) { return __uint_as_float(u << 16); }
; __device__ __forceinline__ float bfhi(unsigned u) { return __uint_as_float(u & 0xffff0000u); }
; __device__ __forceinline__ float siluf_(float v) { return v * __builtin_amdgcn_rcpf(1.0f + __expf(-v)); }
; __device__ __forceinline__ void ssd_item(const Params& p, LAS unsigned char* lds, int bl, int head, int dry) {
;     ...
; #pragma unroll
;             for (int seg = 0; seg < 4; ++seg) {
;                 float val[8][4];
; #pragma unroll
;                 for (int j = 0; j < 8; ++j) { const int i = seg * 8 + j;
;                     const u32x2 x0 = raw[i], x1 = raw[i + 1], x2 = raw[i + 2], x3 = raw[i + 3];
;                     float v0 = cbv[0] + cw0[0] * bflo(x0.x) + cw1[0] * bflo(x1.x) + cw2[0] * bflo(x2.x) + cw3[0] * bflo(x3.x);
;                     float v1 = cbv[1] + cw0[1] * bfhi(x0.x) + cw1[1] * bfhi(x1.x) + cw2[1] * bfhi(x2.x) + cw3[1] * bfhi(x3.x);
;                     float v2 = cbv[2] + cw0[2] * bflo(x0.y) + cw1[2] * bflo(x1.y) + cw2[2] * bflo(x2.y) + cw3[2] * bflo(x3.y);
;                     float v3 = cbv[3] + cw0[3] * bfhi(x0.y) + cw1[3] * bfhi(x1.y) + cw2[3] * bfhi(x2.y) + cw3[3] * bfhi(x3.y);
;                     val[j][0] = siluf_(v0); val[j][1] = siluf_(v1); val[j][2] = siluf_(v2); val[j][3] = siluf_(v3); }
.LBB0_237:
	s_or_b64 exec, exec, vcc
	v_add_u32_e32 v235, s2, v163
	v_max_i32_e32 v242, 0, v235
	v_mad_u64_u32 v[218:219], s[100:101], v242, s33, v[68:69]
	global_load_dwordx2 v[150:151], v[218:219], off
	v_max_i32_e32 v242, -1, v235
	v_add_u32_e32 v242, 1, v242
	v_mad_u64_u32 v[218:219], s[100:101], v242, s33, v[68:69]
	global_load_dwordx2 v[152:153], v[218:219], off
	v_max_i32_e32 v242, -2, v235
	v_add_u32_e32 v242, 2, v242
	v_mad_u64_u32 v[218:219], s[100:101], v242, s33, v[68:69]
	global_load_dwordx2 v[154:155], v[218:219], off
	v_add_u32_e32 v242, 3, v235
	v_mad_i64_i32 v[218:219], s[100:101], v242, s33, v[68:69]
	global_load_dwordx2 v[148:149], v[218:219], off
	v_lshl_add_u64 v[218:219], v[218:219], 0, v[168:169]
	global_load_dwordx2 v[146:147], v[218:219], off
	v_lshl_add_u64 v[218:219], v[218:219], 0, v[168:169]
	global_load_dwordx2 v[144:145], v[218:219], off
	v_lshl_add_u64 v[218:219], v[218:219], 0, v[168:169]
	global_load_dwordx2 v[142:143], v[218:219], off
	v_lshl_add_u64 v[218:219], v[218:219], 0, v[168:169]
	global_load_dwordx2 v[140:141], v[218:219], off
	v_lshl_add_u64 v[218:219], v[218:219], 0, v[168:169]
	global_load_dwordx2 v[138:139], v[218:219], off
	v_lshl_add_u64 v[218:219], v[218:219], 0, v[168:169]
	global_load_dwordx2 v[136:137], v[218:219], off
	v_lshl_add_u64 v[218:219], v[218:219], 0, v[168:169]
	global_load_dwordx2 v[134:135], v[218:219], off
	v_lshl_add_u64 v[218:219], v[218:219], 0, v[168:169]
	global_load_dwordx2 v[132:133], v[218:219], off
	v_lshl_add_u64 v[218:219], v[218:219], 0, v[168:169]
	global_load_dwordx2 v[130:131], v[218:219], off
	v_lshl_add_u64 v[218:219], v[218:219], 0, v[168:169]
	global_load_dwordx2 v[128:129], v[218:219], off
	v_lshl_add_u64 v[218:219], v[218:219], 0, v[168:169]
	global_load_dwordx2 v[126:127], v[218:219], off
	v_lshl_add_u64 v[218:219], v[218:219], 0, v[168:169]
	global_load_dwordx2 v[124:125], v[218:219], off
	v_lshl_add_u64 v[218:219], v[218:219], 0, v[168:169]
	global_load_dwordx2 v[122:123], v[218:219], off
	v_lshl_add_u64 v[218:219], v[218:219], 0, v[168:169]
	global_load_dwordx2 v[120:121], v[218:219], off
	v_lshl_add_u64 v[218:219], v[218:219], 0, v[168:169]
	global_load_dwordx2 v[118:119], v[218:219], off
	v_lshl_add_u64 v[218:219], v[218:219], 0, v[168:169]
	global_load_dwordx2 v[116:117], v[218:219], off
	v_lshl_add_u64 v[218:219], v[218:219], 0, v[168:169]
	global_load_dwordx2 v[114:115], v[218:219], off
	v_lshl_add_u64 v[218:219], v[218:219], 0, v[168:169]
	global_load_dwordx2 v[112:113], v[218:219], off
	v_lshl_add_u64 v[218:219], v[218:219], 0, v[168:169]
	global_load_dwordx2 v[110:111], v[218:219], off
	v_lshl_add_u64 v[218:219], v[218:219], 0, v[168:169]
	global_load_dwordx2 v[108:109], v[218:219], off
	v_fma_f32 v17, v48, v36, v64
	v_fmac_f32_e32 v17, v52, v40
	v_fmac_f32_e32 v17, v56, v44
	s_waitcnt vmcnt(37)
	v_lshlrev_b32_e32 v29, 16, v94
	v_fmac_f32_e32 v17, v60, v29
	v_mul_f32_e32 v19, 0xbfb8aa3b, v17
	v_exp_f32_e32 v19, v19
	v_fma_f32 v18, v49, v37, v65
	v_fmac_f32_e32 v18, v53, v41
	v_fmac_f32_e32 v18, v57, v45
	v_add_f32_e32 v19, 1.0, v19
	v_rcp_f32_e32 v19, v19
	v_and_b32_e32 v30, 0xffff0000, v94
	v_fmac_f32_e32 v18, v61, v30
	v_fma_f32 v20, v50, v38, v66
	v_mul_f32_e32 v17, v17, v19
	v_mul_f32_e32 v19, 0xbfb8aa3b, v18
	v_exp_f32_e32 v19, v19
	v_fmac_f32_e32 v20, v54, v42
	v_fmac_f32_e32 v20, v58, v46
	v_lshlrev_b32_e32 v31, 16, v95
	v_add_f32_e32 v19, 1.0, v19
	v_rcp_f32_e32 v19, v19
	v_fmac_f32_e32 v20, v62, v31
	v_fma_f32 v21, v51, v39, v67
	v_fmac_f32_e32 v21, v55, v43
	v_mul_f32_e32 v19, v18, v19
	v_mul_f32_e32 v18, 0xbfb8aa3b, v20
	v_exp_f32_e32 v18, v18
	v_fmac_f32_e32 v21, v59, v47
	v_and_b32_e32 v32, 0xffff0000, v95
	v_fmac_f32_e32 v21, v63, v32
	v_add_f32_e32 v18, 1.0, v18
	v_rcp_f32_e32 v18, v18
	s_waitcnt vmcnt(36)
	v_lshlrev_b32_e32 v33, 16, v92
	v_fma_f32 v22, v49, v41, v65
	v_fmac_f32_e32 v22, v53, v45
	v_mul_f32_e32 v18, v20, v18
	v_mul_f32_e32 v20, 0xbfb8aa3b, v21
	v_exp_f32_e32 v20, v20
	v_fmac_f32_e32 v22, v57, v30
	v_and_b32_e32 v34, 0xffff0000, v92
	v_fmac_f32_e32 v22, v61, v34
	v_add_f32_e32 v20, 1.0, v20
	v_rcp_f32_e32 v20, v20
	v_fma_f32 v24, v50, v42, v66
	v_fmac_f32_e32 v24, v54, v46
	v_fmac_f32_e32 v24, v58, v31
	v_mul_f32_e32 v20, v21, v20
	v_fma_f32 v21, v48, v40, v64
	v_fmac_f32_e32 v21, v52, v44
	v_fmac_f32_e32 v21, v56, v29
	v_fmac_f32_e32 v21, v60, v33
	v_mul_f32_e32 v23, 0xbfb8aa3b, v21
	v_exp_f32_e32 v23, v23
	v_lshlrev_b32_e32 v35, 16, v93
	v_fmac_f32_e32 v24, v62, v35
	v_fma_f32 v25, v51, v43, v67
	v_add_f32_e32 v23, 1.0, v23
	v_rcp_f32_e32 v23, v23
	v_fmac_f32_e32 v25, v55, v47
	v_fmac_f32_e32 v25, v59, v32
	v_and_b32_e32 v36, 0xffff0000, v93
	v_mul_f32_e32 v21, v21, v23
	v_mul_f32_e32 v23, 0xbfb8aa3b, v22
	v_exp_f32_e32 v23, v23
	v_fmac_f32_e32 v25, v63, v36
	s_waitcnt vmcnt(35)
	v_lshlrev_b32_e32 v37, 16, v88
	v_fma_f32 v26, v49, v45, v65
	v_add_f32_e32 v23, 1.0, v23
	v_rcp_f32_e32 v23, v23
	v_fmac_f32_e32 v26, v53, v30
	v_fmac_f32_e32 v26, v57, v34
	v_and_b32_e32 v38, 0xffff0000, v88
	v_mul_f32_e32 v23, v22, v23
	v_mul_f32_e32 v22, 0xbfb8aa3b, v24
	v_exp_f32_e32 v22, v22
	v_fmac_f32_e32 v26, v61, v38
	v_fma_f32 v28, v50, v46, v66
	v_fmac_f32_e32 v28, v54, v31
	v_add_f32_e32 v22, 1.0, v22
	v_rcp_f32_e32 v22, v22
	v_fmac_f32_e32 v28, v58, v35
	v_lshlrev_b32_e32 v39, 16, v89
	v_fmac_f32_e32 v28, v62, v39
	v_mul_f32_e32 v22, v24, v22
	v_mul_f32_e32 v24, 0xbfb8aa3b, v25
	v_exp_f32_e32 v24, v24
	v_fma_f32 v40, v51, v47, v67
	v_fmac_f32_e32 v40, v55, v32
	v_fmac_f32_e32 v40, v59, v36
	v_add_f32_e32 v24, 1.0, v24
	v_rcp_f32_e32 v24, v24
	v_and_b32_e32 v41, 0xffff0000, v89
	v_fmac_f32_e32 v40, v63, v41
	s_waitcnt vmcnt(34)
; __device__ __forceinline__ float bflo(unsigned u) { return __uint_as_float(u << 16); }
; __device__ __forceinline__ float bfhi(unsigned u) { return __uint_as_float(u & 0xffff0000u); }
; __device__ __forceinline__ float siluf_(float v) { return v * __builtin_amdgcn_rcpf(1.0f + __expf(-v)); }
; __device__ __forceinline__ void ssd_item(const Params& p, LAS unsigned char* lds, int bl, int head, int dry) {
;     ...
;                 for (int j = 0; j < 8; ++j) { const int i = seg * 8 + j;
;                     const u32x2 x0 = raw[i], x1 = raw[i + 1], x2 = raw[i + 2], x3 = raw[i + 3];
;                     float v0 = cbv[0] + cw0[0] * bflo(x0.x) + cw1[0] * bflo(x1.x) + cw2[0] * bflo(x2.x) + cw3[0] * bflo(x3.x);
;                     float v1 = cbv[1] + cw0[1] * bfhi(x0.x) + cw1[1] * bfhi(x1.x) + cw2[1] * bfhi(x2.x) + cw3[1] * bfhi(x3.x);
;                     float v2 = cbv[2] + cw0[2] * bflo(x0.y) + cw1[2] * bflo(x1.y) + cw2[2] * bflo(x2.y) + cw3[2] * bflo(x3.y);
;                     float v3 = cbv[3] + cw0[3] * bfhi(x0.y) + cw1[3] * bfhi(x1.y) + cw2[3] * bfhi(x2.y) + cw3[3] * bfhi(x3.y);
;                     val[j][0] = siluf_(v0); val[j][1] = siluf_(v1); val[j][2] = siluf_(v2); val[j][3] = siluf_(v3); }
	v_lshlrev_b32_e32 v42, 16, v86
	v_mul_f32_e32 v24, v25, v24
	v_fma_f32 v25, v48, v44, v64
	v_fmac_f32_e32 v25, v52, v29
	v_fmac_f32_e32 v25, v56, v33
	v_fmac_f32_e32 v25, v60, v37
	v_mul_f32_e32 v27, 0xbfb8aa3b, v25
	v_exp_f32_e32 v27, v27
	v_fma_f32 v29, v48, v29, v64
	v_fmac_f32_e32 v29, v52, v33
	v_fmac_f32_e32 v29, v56, v37
	v_add_f32_e32 v27, 1.0, v27
	v_rcp_f32_e32 v27, v27
	v_fmac_f32_e32 v29, v60, v42
	v_fma_f32 v30, v49, v30, v65
	v_fmac_f32_e32 v30, v53, v34
	v_mul_f32_e32 v25, v25, v27
	v_mul_f32_e32 v27, 0xbfb8aa3b, v26
	v_exp_f32_e32 v27, v27
	v_fmac_f32_e32 v30, v57, v38
	v_and_b32_e32 v43, 0xffff0000, v86
	v_fmac_f32_e32 v30, v61, v43
	v_add_f32_e32 v27, 1.0, v27
	v_rcp_f32_e32 v27, v27
	v_lshlrev_b32_e32 v44, 16, v87
	v_fma_f32 v32, v51, v32, v67
	v_fmac_f32_e32 v32, v55, v36
	v_mul_f32_e32 v27, v26, v27
	v_mul_f32_e32 v26, 0xbfb8aa3b, v28
	v_exp_f32_e32 v26, v26
	v_fmac_f32_e32 v32, v59, v41
	v_and_b32_e32 v45, 0xffff0000, v87
	v_fmac_f32_e32 v32, v63, v45
	v_add_f32_e32 v26, 1.0, v26
	v_rcp_f32_e32 v26, v26
	v_fma_f32 v33, v48, v33, v64
	v_fmac_f32_e32 v33, v52, v37
	v_fmac_f32_e32 v33, v56, v42
	v_mul_f32_e32 v26, v28, v26
	v_mul_f32_e32 v28, 0xbfb8aa3b, v40
	v_exp_f32_e32 v28, v28
	s_waitcnt vmcnt(33)
	v_lshlrev_b32_e32 v46, 16, v84
	v_fmac_f32_e32 v33, v60, v46
	v_fma_f32 v34, v49, v34, v65
	v_add_f32_e32 v28, 1.0, v28
	v_rcp_f32_e32 v28, v28
	v_fmac_f32_e32 v34, v53, v38
	v_fmac_f32_e32 v34, v57, v43
	v_and_b32_e32 v47, 0xffff0000, v84
	v_mul_f32_e32 v28, v40, v28
	v_fma_f32 v40, v50, v31, v66
	v_mul_f32_e32 v31, 0xbfb8aa3b, v29
	v_exp_f32_e32 v31, v31
	v_fmac_f32_e32 v40, v54, v35
	v_fmac_f32_e32 v40, v58, v39
	v_fmac_f32_e32 v40, v62, v44
	v_add_f32_e32 v31, 1.0, v31
	v_rcp_f32_e32 v31, v31
	v_fmac_f32_e32 v34, v61, v47
	v_lshlrev_b32_e32 v84, 16, v85
	v_fma_f32 v36, v51, v36, v67
	v_mul_f32_e32 v29, v29, v31
	v_mul_f32_e32 v31, 0xbfb8aa3b, v30
	v_exp_f32_e32 v31, v31
	v_fmac_f32_e32 v36, v55, v41
	v_fmac_f32_e32 v36, v59, v45
	v_and_b32_e32 v85, 0xffff0000, v85
	v_add_f32_e32 v31, 1.0, v31
	v_rcp_f32_e32 v31, v31
	v_fmac_f32_e32 v36, v63, v85
	v_fma_f32 v37, v48, v37, v64
	v_fmac_f32_e32 v37, v52, v42
	v_mul_f32_e32 v31, v30, v31
	v_mul_f32_e32 v30, 0xbfb8aa3b, v40
	v_exp_f32_e32 v30, v30
	v_fmac_f32_e32 v37, v56, v46
	s_waitcnt vmcnt(32)
	v_lshlrev_b32_e32 v86, 16, v82
	v_fmac_f32_e32 v37, v60, v86
	v_add_f32_e32 v30, 1.0, v30
	v_rcp_f32_e32 v30, v30
	v_fma_f32 v38, v49, v38, v65
	v_fmac_f32_e32 v38, v53, v43
	v_fmac_f32_e32 v38, v57, v47
	v_mul_f32_e32 v30, v40, v30
	v_mul_f32_e32 v40, 0xbfb8aa3b, v32
	v_exp_f32_e32 v40, v40
	v_and_b32_e32 v82, 0xffff0000, v82
	v_fmac_f32_e32 v38, v61, v82
	v_lshlrev_b32_e32 v87, 16, v83
	v_add_f32_e32 v40, 1.0, v40
	v_rcp_f32_e32 v40, v40
	v_fma_f32 v41, v51, v41, v67
	v_fmac_f32_e32 v41, v55, v45
	v_fmac_f32_e32 v41, v59, v85
	v_mul_f32_e32 v32, v32, v40
	v_fma_f32 v40, v50, v35, v66
	v_mul_f32_e32 v35, 0xbfb8aa3b, v33
	v_exp_f32_e32 v35, v35
	v_fmac_f32_e32 v40, v54, v39
	v_fmac_f32_e32 v40, v58, v44
	v_fmac_f32_e32 v40, v62, v84
	v_add_f32_e32 v35, 1.0, v35
	v_rcp_f32_e32 v35, v35
	v_and_b32_e32 v83, 0xffff0000, v83
	v_fmac_f32_e32 v41, v63, v83
	s_waitcnt vmcnt(31)
	v_lshlrev_b32_e32 v88, 16, v80
	v_mul_f32_e32 v33, v33, v35
	v_mul_f32_e32 v35, 0xbfb8aa3b, v34
	v_exp_f32_e32 v35, v35
	v_and_b32_e32 v80, 0xffff0000, v80
	v_lshlrev_b32_e32 v89, 16, v81
	v_fma_f32 v45, v51, v45, v67
	v_add_f32_e32 v35, 1.0, v35
	v_rcp_f32_e32 v35, v35
	v_fmac_f32_e32 v45, v55, v85
	v_fmac_f32_e32 v45, v59, v83
	v_and_b32_e32 v81, 0xffff0000, v81
	v_mul_f32_e32 v35, v34, v35
	v_mul_f32_e32 v34, 0xbfb8aa3b, v40
	v_exp_f32_e32 v34, v34
	v_fmac_f32_e32 v45, v63, v81
	v_add_f32_e32 v34, 1.0, v34
	v_rcp_f32_e32 v34, v34
	s_nop 0
	v_mul_f32_e32 v34, v40, v34
	v_mul_f32_e32 v40, 0xbfb8aa3b, v36
	v_exp_f32_e32 v40, v40
	s_nop 0
	v_add_f32_e32 v40, 1.0, v40
	v_rcp_f32_e32 v40, v40
	s_nop 0
	v_mul_f32_e32 v36, v36, v40
	v_fma_f32 v40, v50, v39, v66
	v_mul_f32_e32 v39, 0xbfb8aa3b, v37
	v_exp_f32_e32 v39, v39
	v_fmac_f32_e32 v40, v54, v44
	v_fmac_f32_e32 v40, v58, v84
	v_fmac_f32_e32 v40, v62, v87
	v_add_f32_e32 v39, 1.0, v39
	v_rcp_f32_e32 v39, v39
	v_fma_f32 v44, v50, v44, v66
	v_fmac_f32_e32 v44, v54, v84
	v_fmac_f32_e32 v44, v58, v87
	v_mul_f32_e32 v37, v37, v39
	v_mul_f32_e32 v39, 0xbfb8aa3b, v38
	v_exp_f32_e32 v39, v39
	v_fmac_f32_e32 v44, v62, v89
	v_add_f32_e32 v39, 1.0, v39
	v_rcp_f32_e32 v39, v39
	s_nop 0
	v_mul_f32_e32 v39, v38, v39
	v_mul_f32_e32 v38, 0xbfb8aa3b, v40
	v_exp_f32_e32 v38, v38
	s_nop 0
	v_add_f32_e32 v38, 1.0, v38
	v_rcp_f32_e32 v38, v38
	s_nop 0
	v_mul_f32_e32 v38, v40, v38
	v_mul_f32_e32 v40, 0xbfb8aa3b, v41
	v_exp_f32_e32 v40, v40
	s_nop 0
	v_add_f32_e32 v40, 1.0, v40
	v_rcp_f32_e32 v40, v40
	s_nop 0
	v_mul_f32_e32 v40, v41, v40
	v_fma_f32 v41, v48, v42, v64
	v_fmac_f32_e32 v41, v52, v46
	v_fmac_f32_e32 v41, v56, v86
	v_fmac_f32_e32 v41, v60, v88
	v_fma_f32 v42, v49, v43, v65
	v_mul_f32_e32 v43, 0xbfb8aa3b, v41
	v_exp_f32_e32 v43, v43
	v_fmac_f32_e32 v42, v53, v47
	v_fmac_f32_e32 v42, v57, v82
	v_fmac_f32_e32 v42, v61, v80
	v_add_f32_e32 v43, 1.0, v43
	v_rcp_f32_e32 v43, v43
	s_nop 0
	v_mul_f32_e32 v41, v41, v43
	v_mul_f32_e32 v43, 0xbfb8aa3b, v42
	v_exp_f32_e32 v43, v43
	s_nop 0
	v_add_f32_e32 v43, 1.0, v43
	v_rcp_f32_e32 v43, v43
	s_nop 0
	v_mul_f32_e32 v43, v42, v43
	v_mul_f32_e32 v42, 0xbfb8aa3b, v44
	v_exp_f32_e32 v42, v42
	s_nop 0
	v_add_f32_e32 v42, 1.0, v42
	v_rcp_f32_e32 v42, v42
	s_nop 0
	v_mul_f32_e32 v42, v44, v42
	v_mul_f32_e32 v44, 0xbfb8aa3b, v45
	v_exp_f32_e32 v44, v44
	s_nop 0
	v_add_f32_e32 v44, 1.0, v44
	v_rcp_f32_e32 v44, v44
	s_nop 0
	v_mul_f32_e32 v44, v45, v44
	v_fma_f32 v45, v48, v46, v64
	v_fmac_f32_e32 v45, v52, v86
	v_fmac_f32_e32 v45, v56, v88
	s_waitcnt vmcnt(30)
	v_lshlrev_b32_e32 v46, 16, v78
	v_fmac_f32_e32 v45, v60, v46
	v_fma_f32 v46, v49, v47, v65
	v_fmac_f32_e32 v46, v53, v82
	v_and_b32_e32 v47, 0xffff0000, v78
	v_fma_f32 v78, v50, v84, v66
	v_fmac_f32_e32 v46, v57, v80
	v_fmac_f32_e32 v78, v54, v87
	v_fma_f32 v80, v51, v85, v67
	v_fmac_f32_e32 v46, v61, v47
	v_fmac_f32_e32 v78, v58, v89
	v_lshlrev_b32_e32 v47, 16, v79
	v_fmac_f32_e32 v80, v55, v83
	v_fmac_f32_e32 v78, v62, v47
	v_fmac_f32_e32 v80, v59, v81
	v_and_b32_e32 v47, 0xffff0000, v79
	v_fmac_f32_e32 v80, v63, v47
	v_mul_f32_e32 v47, 0xbfb8aa3b, v45
	v_exp_f32_e32 v47, v47
	s_nop 0
	v_add_f32_e32 v47, 1.0, v47
	v_rcp_f32_e32 v47, v47
	s_nop 0
	v_mul_f32_e32 v45, v45, v47
	v_mul_f32_e32 v47, 0xbfb8aa3b, v46
	v_exp_f32_e32 v47, v47
	s_nop 0
	v_add_f32_e32 v47, 1.0, v47
	v_rcp_f32_e32 v47, v47
	s_nop 0
	v_mul_f32_e32 v47, v46, v47
	v_mul_f32_e32 v46, 0xbfb8aa3b, v78
	v_exp_f32_e32 v46, v46
	s_nop 0
	v_add_f32_e32 v46, 1.0, v46
	v_rcp_f32_e32 v46, v46
	s_nop 0
	v_mul_f32_e32 v46, v78, v46
	v_mul_f32_e32 v78, 0xbfb8aa3b, v80
	v_exp_f32_e32 v78, v78
	s_nop 0
	v_add_f32_e32 v78, 1.0, v78
	v_rcp_f32_e32 v78, v78
	s_nop 0
	v_mul_f32_e32 v78, v80, v78
	s_and_saveexec_b64 vcc, s[38:39]
	s_cbranch_execz .LBB0_239
; __device__ __forceinline__ unsigned cvt_pk_bf16(float lo, float hi) { unsigned r; asm volatile("v_cvt_pk_bf16_f32 %0, %1, %2" : "=v"(r) : "v"(lo), "v"(hi)); return r; }
; #define LAS __attribute__((address_space(3)))
; __device__ __forceinline__ void ssd_item(const Params& p, LAS unsigned char* lds, int bl, int head, int dry) {
;     ...
;                 if (kind != 0) { LAS bf16_t* rm = (kind == 1 ? BMm : CM) + lb * SLD + n4;
; #pragma unroll
;                     for (int j = 0; j < 8; ++j) { u32x2 o; o.x = cvt_pk_bf16(val[j][0], val[j][1]); o.y = cvt_pk_bf16(val[j][2], val[j][3]); *(LAS u32x2*)(rm + j * SLD) = o; } }
	v_cvt_pk_bf16_f32 v80, v17, v19
	v_cvt_pk_bf16_f32 v81, v18, v20
	ds_write_b64 v191, v[80:81] offset:4352
	v_cvt_pk_bf16_f32 v80, v21, v23
	v_cvt_pk_bf16_f32 v81, v22, v24
	ds_write_b64 v191, v[80:81] offset:4624
	v_cvt_pk_bf16_f32 v80, v25, v27
	v_cvt_pk_bf16_f32 v81, v26, v28
	ds_write_b64 v191, v[80:81] offset:4896
	v_cvt_pk_bf16_f32 v80, v29, v31
	v_cvt_pk_bf16_f32 v81, v30, v32
	ds_write_b64 v191, v[80:81] offset:5168
	v_cvt_pk_bf16_f32 v80, v33, v35
	v_cvt_pk_bf16_f32 v81, v34, v36
	ds_write_b64 v191, v[80:81] offset:5440
	v_cvt_pk_bf16_f32 v80, v37, v39
	v_cvt_pk_bf16_f32 v81, v38, v40
	ds_write_b64 v191, v[80:81] offset:5712
	v_cvt_pk_bf16_f32 v80, v41, v43
	v_cvt_pk_bf16_f32 v81, v42, v44
	ds_write_b64 v191, v[80:81] offset:5984
	v_cvt_pk_bf16_f32 v80, v45, v47
	v_cvt_pk_bf16_f32 v81, v46, v78
	ds_write_b64 v191, v[80:81] offset:6256

; __device__ __forceinline__ void ssd_item(const Params& p, LAS unsigned char* lds, int bl, int head, int dry) {
;     ...
;         SSD_ISSUE_RAW(c + 1 < 32 ? c + 1 : 31);
.LBB0_242:
	s_or_b64 exec, exec, s[56:57]
	s_cmp_lt_u32 s98, 4
	s_cbranch_scc1 .Lrows_hi
	v_max_i32_e32 v17, 0, v16
	v_mad_u64_u32 v[18:19], s[56:57], v17, s33, v[68:69]
	v_max_i32_e32 v17, -1, v16
	v_add_u32_e32 v17, 1, v17
	v_mad_u64_u32 v[20:21], s[56:57], v17, s33, v[68:69]
	v_max_i32_e32 v17, -2, v16
	v_add_u32_e32 v17, 2, v17
	v_add_u32_e32 v16, 3, v16
	v_mad_u64_u32 v[22:23], s[56:57], v17, s33, v[68:69]
	v_mad_i64_i32 v[16:17], s[56:57], v16, s33, v[68:69]
	global_load_dwordx2 v[150:151], v[18:19], off
	global_load_dwordx2 v[152:153], v[20:21], off
	global_load_dwordx2 v[154:155], v[22:23], off
	global_load_dwordx2 v[148:149], v[16:17], off
	v_lshl_add_u64 v[16:17], v[16:17], 0, v[168:169]
	v_lshl_add_u64 v[18:19], v[16:17], 0, v[168:169]
	v_lshl_add_u64 v[20:21], v[18:19], 0, v[168:169]
	global_load_dwordx2 v[146:147], v[16:17], off
	global_load_dwordx2 v[144:145], v[18:19], off
	global_load_dwordx2 v[142:143], v[20:21], off
	v_lshl_add_u64 v[16:17], v[20:21], 0, v[168:169]
	global_load_dwordx2 v[140:141], v[16:17], off
	v_lshl_add_u64 v[16:17], v[16:17], 0, v[168:169]
	global_load_dwordx2 v[138:139], v[16:17], off
	v_lshl_add_u64 v[16:17], v[16:17], 0, v[168:169]
	global_load_dwordx2 v[136:137], v[16:17], off
	v_lshl_add_u64 v[16:17], v[16:17], 0, v[168:169]
	global_load_dwordx2 v[134:135], v[16:17], off
	s_branch .Lrows_done
.Lrows_hi:
	v_lshl_add_u64 v[218:219], v[218:219], 0, v[168:169]
	global_load_dwordx2 v[106:107], v[218:219], off
	v_lshl_add_u64 v[218:219], v[218:219], 0, v[168:169]
	global_load_dwordx2 v[102:103], v[218:219], off
	v_lshl_add_u64 v[218:219], v[218:219], 0, v[168:169]
	global_load_dwordx2 v[100:101], v[218:219], off
	v_lshl_add_u64 v[218:219], v[218:219], 0, v[168:169]
	global_load_dwordx2 v[94:95], v[218:219], off
	v_lshl_add_u64 v[218:219], v[218:219], 0, v[168:169]
	global_load_dwordx2 v[92:93], v[218:219], off
	v_lshl_add_u64 v[218:219], v[218:219], 0, v[168:169]
	global_load_dwordx2 v[88:89], v[218:219], off
	v_lshl_add_u64 v[218:219], v[218:219], 0, v[168:169]
	global_load_dwordx2 v[86:87], v[218:219], off
	v_lshl_add_u64 v[218:219], v[218:219], 0, v[168:169]
	global_load_dwordx2 v[84:85], v[218:219], off
	v_lshl_add_u64 v[218:219], v[218:219], 0, v[168:169]
	global_load_dwordx2 v[82:83], v[218:219], off
	v_lshl_add_u64 v[218:219], v[218:219], 0, v[168:169]
	global_load_dwordx2 v[80:81], v[218:219], off
	v_lshl_add_u64 v[218:219], v[218:219], 0, v[168:169]
	global_load_dwordx2 v[78:79], v[218:219], off
